# row passes: LayerNorm gain/bias hoisted out of the row loop, rotary table and q/k element loads of a row issued in one batch (rowpass A and B)
# speedup vs baseline: 1.0374x; 1.0141x over previous
.LBB0_138:
	s_and_b32 s0, s16, 0x7ff
	s_cmpk_lt_i32 s16, 0x4000
	s_cselect_b64 s[8:9], -1, 0
	s_and_b64 s[10:11], s[8:9], exec
	s_cselect_b32 s12, s0, s17
	s_cmpk_gt_u32 s0, 0x77f
	s_cselect_b64 s[10:11], -1, 0
	s_and_b64 s[10:11], s[8:9], s[10:11]
	s_ashr_i32 s8, s16, 4
	s_and_b32 s8, s8, 0xffffff80
	s_add_i32 s8, s0, s8
	s_lshl_b32 s0, s12, 8
	v_lshl_add_u64 v[26:27], v[16:17], 0, s[0:1]
	v_lshl_add_u64 v[0:1], s[6:7], 0, v[22:23]
	s_mov_b32 s0, 0xc700000
	v_add_co_u32_e32 v8, vcc, s0, v0
	s_addk_i32 s8, 0xf880
	s_nop 0
	v_addc_co_u32_e32 v9, vcc, 0, v1, vcc
	flat_load_dwordx4 v[4:7], v[8:9]
	flat_load_dwordx4 v[0:3], v[8:9] offset:64
	s_waitcnt lgkmcnt(0)
	flat_load_dwordx4 v[10:13], v[26:27]
	global_load_dwordx4 v[60:63], v[26:27], off offset:16
	global_load_dwordx4 v[64:67], v[26:27], off offset:32
	global_load_dwordx4 v[68:71], v[26:27], off offset:48
	s_ashr_i32 s9, s8, 31
	s_lshl_b64 s[8:9], s[8:9], 10
	s_mov_b64 s[14:15], -1
	s_waitcnt vmcnt(0) lgkmcnt(0)
	v_lshlrev_b32_e32 v14, 16, v4
	v_lshlrev_b32_e32 v28, 16, v0
	v_and_b32_e32 v29, 0xffff0000, v0
	v_mov_b32_e32 v30, v10
	v_mov_b32_e32 v31, v12
	v_mov_b32_e32 v12, v11
	v_and_b32_e32 v15, 0xffff0000, v4
	v_pk_mul_f32 v[10:11], v[12:13], v[28:29]
	v_pk_mul_f32 v[28:29], v[30:31], v[28:29]
	v_pk_fma_f32 v[10:11], v[30:31], v[14:15], v[10:11] neg_lo:[0,0,1] neg_hi:[0,0,1]
	v_pk_fma_f32 v[12:13], v[12:13], v[14:15], v[28:29]
	v_cvt_pk_bf16_f32 v4, v10, v11
	v_cvt_pk_bf16_f32 v0, v12, v13
	v_mov_b32_e32 v10, v60
	v_mov_b32_e32 v11, v61
	v_mov_b32_e32 v12, v62
	v_mov_b32_e32 v13, v63
	v_lshlrev_b32_e32 v28, 16, v1
	v_and_b32_e32 v29, 0xffff0000, v1
	v_lshlrev_b32_e32 v14, 16, v5
	v_and_b32_e32 v15, 0xffff0000, v5
	v_mov_b32_e32 v30, v10
	v_mov_b32_e32 v31, v12
	v_mov_b32_e32 v12, v11
	v_pk_mul_f32 v[10:11], v[12:13], v[28:29]
	v_pk_mul_f32 v[28:29], v[30:31], v[28:29]
	v_pk_fma_f32 v[10:11], v[30:31], v[14:15], v[10:11] neg_lo:[0,0,1] neg_hi:[0,0,1]
	v_pk_fma_f32 v[12:13], v[12:13], v[14:15], v[28:29]
	v_cvt_pk_bf16_f32 v5, v10, v11
	v_cvt_pk_bf16_f32 v1, v12, v13
	v_mov_b32_e32 v10, v64
	v_mov_b32_e32 v11, v65
	v_mov_b32_e32 v12, v66
	v_mov_b32_e32 v13, v67
	v_lshlrev_b32_e32 v28, 16, v2
	v_and_b32_e32 v29, 0xffff0000, v2
	v_lshlrev_b32_e32 v14, 16, v6
	v_and_b32_e32 v15, 0xffff0000, v6
	v_mov_b32_e32 v30, v10
	v_mov_b32_e32 v31, v12
	v_mov_b32_e32 v12, v11
	v_pk_mul_f32 v[10:11], v[12:13], v[28:29]
	v_pk_mul_f32 v[28:29], v[30:31], v[28:29]
	v_pk_fma_f32 v[10:11], v[30:31], v[14:15], v[10:11] neg_lo:[0,0,1] neg_hi:[0,0,1]
	v_pk_fma_f32 v[12:13], v[12:13], v[14:15], v[28:29]
	v_cvt_pk_bf16_f32 v6, v10, v11
	v_cvt_pk_bf16_f32 v2, v12, v13
	v_mov_b32_e32 v10, v68
	v_mov_b32_e32 v11, v69
	v_mov_b32_e32 v12, v70
	v_mov_b32_e32 v13, v71
	v_lshlrev_b32_e32 v28, 16, v3
	v_and_b32_e32 v29, 0xffff0000, v3
	v_lshlrev_b32_e32 v14, 16, v7
	v_and_b32_e32 v15, 0xffff0000, v7
	v_mov_b32_e32 v31, v12
	v_mov_b32_e32 v12, v11
	v_mov_b32_e32 v30, v10
	v_pk_mul_f32 v[10:11], v[12:13], v[28:29]
	v_pk_mul_f32 v[28:29], v[30:31], v[28:29]
	v_pk_fma_f32 v[10:11], v[30:31], v[14:15], v[10:11] neg_lo:[0,0,1] neg_hi:[0,0,1]
	v_pk_fma_f32 v[12:13], v[12:13], v[14:15], v[28:29]
	v_cvt_pk_bf16_f32 v7, v10, v11
	v_cvt_pk_bf16_f32 v3, v12, v13
	flat_store_dwordx4 v[8:9], v[4:7]
	flat_store_dwordx4 v[8:9], v[0:3] offset:64
	s_and_saveexec_b64 s[12:13], s[4:5]
	s_cbranch_execz .LBB0_142
	v_lshl_add_u64 v[0:1], s[6:7], 0, v[24:25]
	v_add_co_u32_e32 v28, vcc, 0xc700000, v0
	s_mov_b64 s[14:15], 0
	s_nop 0
	v_addc_co_u32_e32 v29, vcc, 0, v1, vcc
	flat_load_dwordx4 v[12:15], v[28:29]
	flat_load_dwordx4 v[8:11], v[28:29] offset:64
	flat_load_dwordx4 v[0:3], v[26:27]
	flat_load_dwordx4 v[36:39], v[26:27] offset:16
	s_and_b64 vcc, exec, s[10:11]
	s_waitcnt vmcnt(0) lgkmcnt(0)
	v_lshlrev_b32_e32 v6, 16, v12
	v_lshlrev_b32_e32 v30, 16, v8
	v_and_b32_e32 v31, 0xffff0000, v8
	v_mov_b32_e32 v33, v2
	v_mov_b32_e32 v2, v1
	v_and_b32_e32 v7, 0xffff0000, v12
	v_mov_b32_e32 v32, v0
	v_pk_mul_f32 v[0:1], v[2:3], v[30:31]
	v_lshlrev_b32_e32 v8, 16, v9
	v_pk_fma_f32 v[4:5], v[32:33], v[6:7], v[0:1] neg_lo:[0,0,1] neg_hi:[0,0,1]
	v_pk_mul_f32 v[0:1], v[32:33], v[30:31]
	v_and_b32_e32 v9, 0xffff0000, v9
	v_pk_fma_f32 v[0:1], v[2:3], v[6:7], v[0:1]
	v_lshlrev_b32_e32 v2, 16, v13
	v_and_b32_e32 v3, 0xffff0000, v13
	v_mov_b32_e32 v12, v36
	v_mov_b32_e32 v13, v38
	v_mov_b32_e32 v38, v37
	v_pk_mul_f32 v[6:7], v[38:39], v[8:9]
	v_pk_mul_f32 v[8:9], v[12:13], v[8:9]
	v_pk_fma_f32 v[6:7], v[12:13], v[2:3], v[6:7] neg_lo:[0,0,1] neg_hi:[0,0,1]
	v_pk_fma_f32 v[2:3], v[38:39], v[2:3], v[8:9]
	v_mov_b32_e32 v36, v64
	v_mov_b32_e32 v37, v65
	v_mov_b32_e32 v38, v66
	v_mov_b32_e32 v39, v67
	v_lshlrev_b32_e32 v32, 16, v10
	v_and_b32_e32 v33, 0xffff0000, v10
	v_lshlrev_b32_e32 v8, 16, v14
	v_and_b32_e32 v9, 0xffff0000, v14
	v_lshlrev_b32_e32 v10, 16, v11
	v_and_b32_e32 v11, 0xffff0000, v11
	v_cvt_pk_bf16_f32 v30, v4, v5
	v_cvt_pk_bf16_f32 v31, v6, v7
	v_cvt_pk_bf16_f32 v34, v0, v1
	v_cvt_pk_bf16_f32 v35, v2, v3
	v_mov_b32_e32 v40, v36
	v_mov_b32_e32 v41, v38
	v_mov_b32_e32 v38, v37
	v_pk_mul_f32 v[12:13], v[38:39], v[32:33]
	v_pk_mul_f32 v[32:33], v[40:41], v[32:33]
	v_pk_fma_f32 v[12:13], v[40:41], v[8:9], v[12:13] neg_lo:[0,0,1] neg_hi:[0,0,1]
	v_pk_fma_f32 v[8:9], v[38:39], v[8:9], v[32:33]
	v_mov_b32_e32 v38, v68
	v_mov_b32_e32 v39, v69
	v_mov_b32_e32 v40, v70
	v_mov_b32_e32 v41, v71
	v_lshlrev_b32_e32 v26, 16, v15
	v_and_b32_e32 v27, 0xffff0000, v15
	v_cvt_pk_bf16_f32 v32, v12, v13
	v_cvt_pk_bf16_f32 v36, v8, v9
	v_mov_b32_e32 v43, v40
	v_mov_b32_e32 v40, v39
	v_mov_b32_e32 v42, v38
	v_pk_mul_f32 v[14:15], v[40:41], v[10:11]
	v_pk_mul_f32 v[10:11], v[42:43], v[10:11]
	v_pk_fma_f32 v[14:15], v[42:43], v[26:27], v[14:15] neg_lo:[0,0,1] neg_hi:[0,0,1]
	v_pk_fma_f32 v[10:11], v[40:41], v[26:27], v[10:11]
	v_cvt_pk_bf16_f32 v33, v14, v15
	v_cvt_pk_bf16_f32 v37, v10, v11
	flat_store_dwordx4 v[28:29], v[30:33]
	flat_store_dwordx4 v[28:29], v[34:37] offset:64
	s_cbranch_vccz .LBB0_141
	v_lshl_add_u64 v[26:27], v[20:21], 0, s[8:9]
	v_add_co_u32_e32 v26, vcc, 0xabff000, v26
	s_mov_b64 s[14:15], -1
	s_nop 0
	v_addc_co_u32_e32 v27, vcc, 0, v27, vcc
	flat_store_dwordx4 v[26:27], v[4:7]
	flat_store_dwordx4 v[26:27], v[12:15] offset:16
	flat_store_dwordx4 v[26:27], v[0:3] offset:128
	flat_store_dwordx4 v[26:27], v[8:11] offset:144

.LBB0_385:
	s_andn2_b64 vcc, exec, s[4:5]
	s_cbranch_vccnz .LBB0_451
	s_cmp_gt_i32 s72, 1
	s_mov_b64 s[4:5], -1
	s_cbranch_scc0 .LBB0_395
	v_readlane_b32 s0, v252, 10
	v_readlane_b32 s6, v254, 58
	s_add_i32 s14, s6, s0
	s_mov_b64 s[4:5], s[94:95]
	s_mov_b64 s[8:9], s[92:93]
	s_cmpk_gt_i32 s14, 0x43ff
	s_cbranch_scc1 .LBB0_394
	v_and_b32_e32 v0, 64, v188
	v_add_u32_e32 v0, 64, v0
	v_xor_b32_e32 v1, 1, v188
	v_cmp_lt_i32_e32 vcc, v1, v0
	s_add_u32 s6, s4, 0x4400000
	s_addc_u32 s7, s5, 0
	v_cndmask_b32_e32 v1, v188, v1, vcc
	v_lshlrev_b32_e32 v9, 2, v1
	v_xor_b32_e32 v1, 2, v188
	v_cmp_lt_i32_e32 vcc, v1, v0
	s_add_u32 s15, s8, 0xa800000
	s_addc_u32 s16, s9, 0
	v_cndmask_b32_e32 v1, v188, v1, vcc
	v_lshlrev_b32_e32 v30, 2, v1
	v_xor_b32_e32 v1, 4, v188
	v_cmp_lt_i32_e32 vcc, v1, v0
	s_mov_b64 s[8:9], s[80:81]
	v_readlane_b32 s72, v252, 12
	v_cndmask_b32_e32 v1, v188, v1, vcc
	v_lshlrev_b32_e32 v31, 2, v1
	v_xor_b32_e32 v1, 8, v188
	v_cmp_lt_i32_e32 vcc, v1, v0
	s_bfe_u32 s17, s69, 0x30006
	v_readlane_b32 s80, v252, 20
	v_cndmask_b32_e32 v1, v188, v1, vcc
	v_lshlrev_b32_e32 v32, 2, v1
	v_xor_b32_e32 v1, 16, v188
	v_cmp_lt_i32_e32 vcc, v1, v0
	v_readlane_b32 s81, v252, 21
	v_lshlrev_b32_e32 v152, 5, v192
	v_cndmask_b32_e32 v1, v188, v1, vcc
	v_lshlrev_b32_e32 v33, 2, v1
	v_xor_b32_e32 v1, 32, v188
	v_cmp_lt_i32_e32 vcc, v1, v0
	v_readlane_b32 s76, v252, 16
	v_readlane_b32 s77, v252, 17
	v_readlane_b32 s78, v252, 18
	v_readlane_b32 s79, v252, 19
	v_readlane_b32 s84, v252, 24
	v_readlane_b32 s85, v252, 25
	s_mov_b64 s[80:81], s[8:9]
	s_bitset1_b32 s17, 11
	s_mul_i32 s8, s14, 0x2800
	v_cndmask_b32_e32 v0, v188, v1, vcc
	v_readlane_b32 s83, v252, 23
	v_readlane_b32 s86, v252, 26
	v_readlane_b32 s87, v252, 27
	v_readlane_b32 s84, v254, 51
	v_readlane_b32 s88, v254, 43
	v_readlane_b32 s92, v254, 25
	v_lshl_add_u64 v[10:11], s[76:77], 0, v[152:153]
	v_readlane_b32 s76, v254, 47
	s_waitcnt lgkmcnt(0)
	v_lshl_add_u64 v[12:13], s[78:79], 0, v[152:153]
	v_readlane_b32 s78, v254, 45
	s_mul_hi_i32 s0, s14, 0x2800
	s_add_u32 s8, s4, s8
	v_lshlrev_b32_e32 v8, 3, v192
	v_lshlrev_b32_e32 v34, 2, v0
	v_readlane_b32 s72, v254, 57
	v_readlane_b32 s85, v254, 52
	s_mov_b32 s87, 0xf800000
	v_readlane_b32 s86, v254, 50
	v_readlane_b32 s83, v254, 49
	v_readlane_b32 s89, v254, 44
	v_readlane_b32 s93, v254, 26
	v_readlane_b32 s94, v254, 27
	v_readlane_b32 s95, v254, 28
	v_readlane_b32 s77, v254, 48
	v_readlane_b32 s79, v254, 46
	v_lshlrev_b32_e32 v14, 4, v192
	v_mov_b32_e32 v15, v153
	s_addc_u32 s9, s5, s0
	v_lshlrev_b32_e32 v16, 1, v192
	v_mov_b32_e32 v17, v153
	v_readlane_b32 s73, v252, 13
	v_readlane_b32 s74, v252, 14
	v_readlane_b32 s75, v252, 15
	v_readlane_b32 s82, v252, 22
	global_load_dwordx4 v[68:71], v[10:11], off
	global_load_dwordx4 v[72:75], v[10:11], off offset:16
	global_load_dwordx4 v[76:79], v[12:13], off
	global_load_dwordx4 v[80:83], v[12:13], off offset:16
	global_load_dwordx4 v[84:87], v[10:11], off offset:2064
	global_load_dwordx4 v[88:91], v[10:11], off offset:2048
	global_load_dwordx4 v[92:95], v[12:13], off offset:2048
	global_load_dwordx4 v[96:99], v[12:13], off offset:2064
	s_branch .LBB0_390
.LBB0_389:
	s_and_b32 s0, s14, 0x7ff
	s_cmpk_lt_i32 s14, 0x4000
	s_cselect_b32 s0, s0, s17
	v_lshl_or_b32 v152, s0, 9, v8
	v_lshl_add_u64 v[0:1], s[6:7], 0, v[152:153]
	v_mov_b32_e32 v2, v100
	v_mov_b32_e32 v3, v101
	v_lshl_add_u64 v[0:1], s[8:9], 0, v[16:17]
	v_add_co_u32_e32 v0, vcc, 0xc701000, v0
	s_mov_b32 s0, 0x3db504f3
	s_nop 0
	v_addc_co_u32_e32 v1, vcc, 0, v1, vcc
	v_mov_b32_e32 v4, v102
	v_mov_b32_e32 v5, v103
	s_add_i32 s14, s14, s80
	s_waitcnt vmcnt(0)
	v_lshlrev_b32_e32 v4, 16, v4
	v_lshlrev_b32_e32 v6, 16, v5
	v_pk_mul_f32 v[6:7], v[2:3], v[6:7] op_sel:[1,0] op_sel_hi:[0,0]
	v_pk_fma_f32 v[18:19], v[2:3], v[4:5], v[6:7] neg_lo:[0,0,1] neg_hi:[0,0,1]
	v_pk_fma_f32 v[4:5], v[2:3], v[4:5], v[6:7] op_sel_hi:[1,0,1]
	s_nop 0
	v_cvt_pk_bf16_f32 v4, v18, v5
	flat_store_short v[0:1], v4
	flat_store_short_d16_hi v[0:1], v4 offset:128
	v_mov_b32_e32 v4, v104
	s_nop 0
	v_mov_b32_e32 v5, v105
	v_lshlrev_b32_e32 v4, 16, v4
	v_lshlrev_b32_e32 v6, 16, v5
	v_pk_mul_f32 v[6:7], v[2:3], v[6:7] op_sel:[1,0] op_sel_hi:[0,0]
	v_pk_fma_f32 v[18:19], v[2:3], v[4:5], v[6:7] neg_lo:[0,0,1] neg_hi:[0,0,1]
	v_pk_fma_f32 v[4:5], v[2:3], v[4:5], v[6:7] op_sel_hi:[1,0,1]
	s_nop 0
	v_cvt_pk_bf16_f32 v4, v18, v5
	flat_store_short v[0:1], v4 offset:256
	flat_store_short_d16_hi v[0:1], v4 offset:384
	v_mov_b32_e32 v4, v106
	s_nop 0
	v_mov_b32_e32 v5, v107
	v_lshlrev_b32_e32 v4, 16, v4
	v_lshlrev_b32_e32 v6, 16, v5
	v_pk_mul_f32 v[6:7], v[2:3], v[6:7] op_sel:[1,0] op_sel_hi:[0,0]
	v_pk_fma_f32 v[18:19], v[2:3], v[4:5], v[6:7] neg_lo:[0,0,1] neg_hi:[0,0,1]
	v_pk_fma_f32 v[4:5], v[2:3], v[4:5], v[6:7] op_sel_hi:[1,0,1]
	s_nop 0
	v_cvt_pk_bf16_f32 v4, v18, v5
	flat_store_short v[0:1], v4 offset:512
	flat_store_short_d16_hi v[0:1], v4 offset:640
	v_mov_b32_e32 v4, v108
	s_nop 0
	v_mov_b32_e32 v5, v109
	v_lshlrev_b32_e32 v4, 16, v4
	v_lshlrev_b32_e32 v6, 16, v5
	v_pk_mul_f32 v[6:7], v[2:3], v[6:7] op_sel:[1,0] op_sel_hi:[0,0]
	v_pk_fma_f32 v[18:19], v[2:3], v[4:5], v[6:7] neg_lo:[0,0,1] neg_hi:[0,0,1]
	v_pk_fma_f32 v[4:5], v[2:3], v[4:5], v[6:7] op_sel_hi:[1,0,1]
	s_nop 0
	v_cvt_pk_bf16_f32 v4, v18, v5
	flat_store_short v[0:1], v4 offset:768
	flat_store_short_d16_hi v[0:1], v4 offset:896
	v_mov_b32_e32 v4, v110
	s_nop 0
	v_mov_b32_e32 v5, v111
	v_lshlrev_b32_e32 v4, 16, v4
	v_lshlrev_b32_e32 v6, 16, v5
	v_pk_mul_f32 v[6:7], v[2:3], v[6:7] op_sel:[1,0] op_sel_hi:[0,0]
	v_pk_fma_f32 v[18:19], v[2:3], v[4:5], v[6:7] neg_lo:[0,0,1] neg_hi:[0,0,1]
	v_pk_fma_f32 v[4:5], v[2:3], v[4:5], v[6:7] op_sel_hi:[1,0,1]
	s_nop 0
	v_mov_b32_e32 v19, v5
	v_pk_mul_f32 v[4:5], v[18:19], s[0:1] op_sel_hi:[1,0]
	s_nop 0
	v_cvt_pk_bf16_f32 v4, v4, v5
	flat_store_short v[0:1], v4 offset:1024
	flat_store_short_d16_hi v[0:1], v4 offset:1152
	v_mov_b32_e32 v4, v112
	s_nop 0
	v_mov_b32_e32 v5, v113
	v_lshlrev_b32_e32 v4, 16, v4
	v_lshlrev_b32_e32 v6, 16, v5
	v_pk_mul_f32 v[6:7], v[2:3], v[6:7] op_sel:[1,0] op_sel_hi:[0,0]
	v_pk_fma_f32 v[18:19], v[2:3], v[4:5], v[6:7] neg_lo:[0,0,1] neg_hi:[0,0,1]
	v_pk_fma_f32 v[4:5], v[2:3], v[4:5], v[6:7] op_sel_hi:[1,0,1]
	s_nop 0
	v_mov_b32_e32 v19, v5
	v_pk_mul_f32 v[4:5], v[18:19], s[0:1] op_sel_hi:[1,0]
	s_nop 0
	v_cvt_pk_bf16_f32 v4, v4, v5
	flat_store_short v[0:1], v4 offset:1280
	flat_store_short_d16_hi v[0:1], v4 offset:1408
	v_mov_b32_e32 v4, v114
	s_nop 0
	v_mov_b32_e32 v5, v115
	v_lshlrev_b32_e32 v4, 16, v4
	v_lshlrev_b32_e32 v6, 16, v5
	v_pk_mul_f32 v[6:7], v[2:3], v[6:7] op_sel:[1,0] op_sel_hi:[0,0]
	v_pk_fma_f32 v[18:19], v[2:3], v[4:5], v[6:7] neg_lo:[0,0,1] neg_hi:[0,0,1]
	v_pk_fma_f32 v[4:5], v[2:3], v[4:5], v[6:7] op_sel_hi:[1,0,1]
	s_nop 0
	v_mov_b32_e32 v19, v5
	v_pk_mul_f32 v[4:5], v[18:19], s[0:1] op_sel_hi:[1,0]
	s_nop 0
	v_cvt_pk_bf16_f32 v4, v4, v5
	flat_store_short v[0:1], v4 offset:1536
	flat_store_short_d16_hi v[0:1], v4 offset:1664
	v_mov_b32_e32 v4, v116
	s_nop 0
	v_mov_b32_e32 v5, v117
	v_lshlrev_b32_e32 v4, 16, v4
	v_lshlrev_b32_e32 v6, 16, v5
	v_pk_mul_f32 v[6:7], v[2:3], v[6:7] op_sel:[1,0] op_sel_hi:[0,0]
	v_pk_fma_f32 v[18:19], v[2:3], v[4:5], v[6:7] neg_lo:[0,0,1] neg_hi:[0,0,1]
	v_pk_fma_f32 v[2:3], v[2:3], v[4:5], v[6:7] op_sel_hi:[1,0,1]
	s_nop 0
	v_mov_b32_e32 v19, v3
	v_pk_mul_f32 v[2:3], v[18:19], s[0:1] op_sel_hi:[1,0]
	s_mul_i32 s0, s3, 0x14000
	s_add_u32 s8, s8, s0
	s_mul_hi_i32 s0, s80, 0x2800
	s_addc_u32 s9, s9, s0
	v_cvt_pk_bf16_f32 v2, v2, v3
	s_cmpk_gt_i32 s14, 0x43ff
	flat_store_short v[0:1], v2 offset:1792
	flat_store_short_d16_hi v[0:1], v2 offset:1920
	s_cbranch_scc1 .LBB0_394
.LBB0_390:
	s_and_b32 s0, s14, 0x7ff
	s_cmpk_lt_i32 s14, 0x4000
	s_cselect_b32 s0, s0, s17
	v_lshl_or_b32 v152, s0, 9, v8
	v_lshl_add_u64 v[120:121], s[6:7], 0, v[152:153]
	global_load_dwordx2 v[100:101], v[120:121], off
	v_lshl_add_u64 v[118:119], s[8:9], 0, v[16:17]
	v_add_co_u32_e32 v118, vcc, 0xc701000, v118
	s_nop 1
	v_addc_co_u32_e32 v119, vcc, 0, v119, vcc
	global_load_ushort v102, v[118:119], off
	global_load_ushort v103, v[118:119], off offset:128
	global_load_ushort v104, v[118:119], off offset:256
	global_load_ushort v105, v[118:119], off offset:384
	global_load_ushort v106, v[118:119], off offset:512
	global_load_ushort v107, v[118:119], off offset:640
	global_load_ushort v108, v[118:119], off offset:768
	global_load_ushort v109, v[118:119], off offset:896
	global_load_ushort v110, v[118:119], off offset:1024
	global_load_ushort v111, v[118:119], off offset:1152
	global_load_ushort v112, v[118:119], off offset:1280
	global_load_ushort v113, v[118:119], off offset:1408
	global_load_ushort v114, v[118:119], off offset:1536
	global_load_ushort v115, v[118:119], off offset:1664
	global_load_ushort v116, v[118:119], off offset:1792
	global_load_ushort v117, v[118:119], off offset:1920
	v_lshl_add_u64 v[18:19], s[8:9], 0, v[14:15]
	v_add_co_u32_e32 v44, vcc, 0xc700000, v18
	s_cmpk_gt_i32 s14, 0x3fff
	s_nop 0
	v_addc_co_u32_e32 v45, vcc, 0, v19, vcc
	flat_load_dwordx4 v[0:3], v[44:45] offset:3072
	flat_load_dwordx4 v[4:7], v[44:45] offset:2048
	s_cselect_b64 s[10:11], -1, 0
	s_add_i32 s0, s14, 0xffffc000
	s_lshl_b64 s[4:5], s[0:1], 12
	s_add_u32 s12, s15, s4
	s_addc_u32 s13, s16, s5
	s_cmpk_lt_i32 s14, 0x4000
	v_lshlrev_b32_e32 v152, 2, v8
	s_waitcnt vmcnt(0) lgkmcnt(0)
	v_lshlrev_b32_e32 v20, 16, v0
	v_lshlrev_b32_e32 v50, 16, v4
	v_and_b32_e32 v21, 0xffff0000, v0
	v_and_b32_e32 v51, 0xffff0000, v4
	v_add_f32_e32 v0, 0, v50
	v_lshlrev_b32_e32 v46, 16, v5
	v_add_f32_e32 v0, v0, v51
	v_and_b32_e32 v47, 0xffff0000, v5
	v_add_f32_e32 v0, v0, v46
	v_lshlrev_b32_e32 v48, 16, v6
	v_add_f32_e32 v0, v0, v47
	v_and_b32_e32 v49, 0xffff0000, v6
	v_add_f32_e32 v0, v0, v48
	v_lshlrev_b32_e32 v28, 16, v7
	v_add_f32_e32 v0, v0, v49
	v_and_b32_e32 v29, 0xffff0000, v7
	v_add_f32_e32 v0, v0, v28
	v_add_f32_e32 v0, v0, v29
	v_add_f32_e32 v0, v0, v20
	v_lshlrev_b32_e32 v22, 16, v1
	v_add_f32_e32 v0, v0, v21
	v_and_b32_e32 v23, 0xffff0000, v1
	v_add_f32_e32 v0, v0, v22
	v_lshlrev_b32_e32 v24, 16, v2
	v_add_f32_e32 v0, v0, v23
	v_and_b32_e32 v25, 0xffff0000, v2
	v_add_f32_e32 v0, v0, v24
	v_lshlrev_b32_e32 v26, 16, v3
	v_add_f32_e32 v0, v0, v25
	v_and_b32_e32 v27, 0xffff0000, v3
	v_add_f32_e32 v0, v0, v26
	v_add_f32_e32 v0, v0, v27
	ds_bpermute_b32 v1, v9, v0
	s_waitcnt lgkmcnt(0)
	v_add_f32_e32 v0, v0, v1
	ds_bpermute_b32 v1, v30, v0
	s_waitcnt lgkmcnt(0)
	v_add_f32_e32 v0, v0, v1
	ds_bpermute_b32 v1, v31, v0
	s_waitcnt lgkmcnt(0)
	v_add_f32_e32 v0, v0, v1
	ds_bpermute_b32 v1, v32, v0
	s_waitcnt lgkmcnt(0)
	v_add_f32_e32 v0, v0, v1
	ds_bpermute_b32 v1, v33, v0
	s_waitcnt lgkmcnt(0)
	v_add_f32_e32 v35, v0, v1
	ds_bpermute_b32 v52, v34, v35
	v_mov_b32_e32 v0, v68
	v_mov_b32_e32 v1, v69
	v_mov_b32_e32 v2, v70
	v_mov_b32_e32 v3, v71
	v_mov_b32_e32 v36, v72
	v_mov_b32_e32 v37, v73
	v_mov_b32_e32 v38, v74
	v_mov_b32_e32 v39, v75
	v_mov_b32_e32 v4, v76
	v_mov_b32_e32 v5, v77
	v_mov_b32_e32 v6, v78
	v_mov_b32_e32 v7, v79
	v_mov_b32_e32 v40, v80
	v_mov_b32_e32 v41, v81
	v_mov_b32_e32 v42, v82
	v_mov_b32_e32 v43, v83
	s_waitcnt lgkmcnt(0)
	v_add_f32_e32 v35, v35, v52
	v_mul_f32_e32 v52, 0x3a800000, v35
	v_pk_add_f32 v[50:51], v[50:51], v[52:53] op_sel_hi:[1,0] neg_lo:[0,1] neg_hi:[0,1]
	v_pk_add_f32 v[46:47], v[46:47], v[52:53] op_sel_hi:[1,0] neg_lo:[0,1] neg_hi:[0,1]
	v_pk_add_f32 v[54:55], v[28:29], v[52:53] op_sel_hi:[1,0] neg_lo:[0,1] neg_hi:[0,1]
	v_pk_mul_f32 v[28:29], v[50:51], v[50:51]
	v_pk_add_f32 v[48:49], v[48:49], v[52:53] op_sel_hi:[1,0] neg_lo:[0,1] neg_hi:[0,1]
	v_pk_add_f32 v[20:21], v[20:21], v[52:53] op_sel_hi:[1,0] neg_lo:[0,1] neg_hi:[0,1]
	v_pk_add_f32 v[22:23], v[22:23], v[52:53] op_sel_hi:[1,0] neg_lo:[0,1] neg_hi:[0,1]
	v_pk_add_f32 v[24:25], v[24:25], v[52:53] op_sel_hi:[1,0] neg_lo:[0,1] neg_hi:[0,1]
	v_pk_add_f32 v[26:27], v[26:27], v[52:53] op_sel_hi:[1,0] neg_lo:[0,1] neg_hi:[0,1]
	v_pk_mul_f32 v[52:53], v[46:47], v[46:47]
	v_add_f32_e32 v28, v28, v29
	v_add_f32_e32 v28, v52, v28
	v_pk_mul_f32 v[56:57], v[48:49], v[48:49]
	v_add_f32_e32 v28, v53, v28
	v_add_f32_e32 v28, v56, v28
	v_pk_mul_f32 v[58:59], v[54:55], v[54:55]
	v_add_f32_e32 v28, v57, v28
	v_add_f32_e32 v28, v58, v28
	v_pk_mul_f32 v[60:61], v[20:21], v[20:21]
	v_add_f32_e32 v28, v59, v28
	v_add_f32_e32 v28, v60, v28
	v_pk_mul_f32 v[62:63], v[22:23], v[22:23]
	v_add_f32_e32 v28, v61, v28
	v_add_f32_e32 v28, v62, v28
	v_pk_mul_f32 v[64:65], v[24:25], v[24:25]
	v_add_f32_e32 v28, v63, v28
	v_add_f32_e32 v28, v64, v28
	v_pk_mul_f32 v[66:67], v[26:27], v[26:27]
	v_add_f32_e32 v28, v65, v28
	v_add_f32_e32 v28, v66, v28
	v_add_f32_e32 v28, v67, v28
	ds_bpermute_b32 v29, v9, v28
	s_waitcnt lgkmcnt(0)
	v_add_f32_e32 v28, v28, v29
	ds_bpermute_b32 v29, v30, v28
	s_waitcnt lgkmcnt(0)
	v_add_f32_e32 v28, v28, v29
	ds_bpermute_b32 v29, v31, v28
	s_waitcnt lgkmcnt(0)
	v_add_f32_e32 v28, v28, v29
	ds_bpermute_b32 v29, v32, v28
	s_waitcnt lgkmcnt(0)
	v_add_f32_e32 v28, v28, v29
	ds_bpermute_b32 v29, v33, v28
	s_waitcnt lgkmcnt(0)
	v_add_f32_e32 v28, v28, v29
	ds_bpermute_b32 v29, v34, v28
	s_waitcnt lgkmcnt(0)
	v_add_f32_e32 v28, v28, v29
	v_fmamk_f32 v28, v28, 0x3a800000, v183
	v_mul_f32_e32 v29, 0x4f800000, v28
	v_cmp_gt_f32_e32 vcc, s87, v28
	s_nop 1
	v_cndmask_b32_e32 v28, v28, v29, vcc
	v_sqrt_f32_e32 v29, v28
	s_nop 0
	v_add_u32_e32 v35, -1, v29
	v_add_u32_e32 v52, 1, v29
	v_fma_f32 v53, -v35, v29, v28
	v_fma_f32 v56, -v52, v29, v28
	v_cmp_ge_f32_e64 s[4:5], 0, v53
	s_nop 1
	v_cndmask_b32_e64 v29, v29, v35, s[4:5]
	v_cmp_lt_f32_e64 s[4:5], 0, v56
	s_nop 1
	v_cndmask_b32_e64 v29, v29, v52, s[4:5]
	v_mul_f32_e32 v35, 0x37800000, v29
	v_cndmask_b32_e32 v29, v29, v35, vcc
	v_cmp_class_f32_e32 vcc, v28, v189
	s_nop 1
	v_cndmask_b32_e32 v28, v29, v28, vcc
	v_div_scale_f32 v29, s[4:5], v28, v28, 1.0
	v_rcp_f32_e32 v35, v29
	v_div_scale_f32 v52, vcc, 1.0, v28, 1.0
	v_fma_f32 v53, -v29, v35, 1.0
	v_fmac_f32_e32 v35, v53, v35
	v_mul_f32_e32 v53, v52, v35
	v_fma_f32 v56, -v29, v53, v52
	v_fmac_f32_e32 v53, v56, v35
	v_fma_f32 v29, -v29, v53, v52
	v_div_fmas_f32 v29, v29, v35, v53
	v_div_fixup_f32 v28, v29, v28, 1.0
	v_pk_mul_f32 v[50:51], v[50:51], v[28:29] op_sel_hi:[1,0]
	v_pk_mul_f32 v[48:49], v[48:49], v[28:29] op_sel_hi:[1,0]
	v_pk_mul_f32 v[46:47], v[46:47], v[28:29] op_sel_hi:[1,0]
	v_pk_mul_f32 v[52:53], v[54:55], v[28:29] op_sel_hi:[1,0]
	v_pk_fma_f32 v[4:5], v[0:1], v[50:51], v[4:5]
	s_waitcnt vmcnt(0)
	v_pk_fma_f32 v[0:1], v[36:37], v[48:49], v[40:41]
	v_pk_fma_f32 v[6:7], v[2:3], v[46:47], v[6:7]
	v_pk_fma_f32 v[2:3], v[38:39], v[52:53], v[42:43]
	v_cvt_pk_bf16_f32 v36, v4, v5
	v_cvt_pk_bf16_f32 v37, v6, v7
	v_cvt_pk_bf16_f32 v38, v0, v1
	v_cvt_pk_bf16_f32 v39, v2, v3
	flat_store_dwordx4 v[44:45], v[36:39] offset:2048
	s_cbranch_scc1 .LBB0_392
	s_nop 0
	v_lshl_add_u64 v[36:37], s[12:13], 0, v[152:153]
	flat_store_dwordx4 v[36:37], v[4:7] nt
	flat_store_dwordx4 v[36:37], v[0:3] offset:16 nt
.LBB0_392:
	s_nop 1
	v_mov_b32_e32 v0, v84
	v_mov_b32_e32 v1, v85
	v_mov_b32_e32 v2, v86
	v_mov_b32_e32 v3, v87
	s_nop 0
	v_mov_b32_e32 v4, v88
	v_mov_b32_e32 v5, v89
	v_mov_b32_e32 v6, v90
	v_mov_b32_e32 v7, v91
	v_mov_b32_e32 v36, v92
	v_mov_b32_e32 v37, v93
	v_mov_b32_e32 v38, v94
	v_mov_b32_e32 v39, v95
	v_mov_b32_e32 v40, v96
	v_mov_b32_e32 v41, v97
	v_mov_b32_e32 v42, v98
	v_mov_b32_e32 v43, v99
	s_mov_b64 s[4:5], 0xc700c00
	v_mov_b32_e32 v29, v28
	v_lshl_add_u64 v[44:45], v[18:19], 0, s[4:5]
	v_pk_mul_f32 v[18:19], v[20:21], v[28:29]
	v_pk_mul_f32 v[20:21], v[24:25], v[28:29]
	v_pk_mul_f32 v[22:23], v[22:23], v[28:29]
	v_pk_mul_f32 v[24:25], v[26:27], v[28:29]
	s_andn2_b64 vcc, exec, s[10:11]
	s_waitcnt vmcnt(0)
	v_pk_fma_f32 v[4:5], v[18:19], v[4:5], v[36:37]
	v_pk_fma_f32 v[0:1], v[20:21], v[0:1], v[40:41]
	v_pk_fma_f32 v[6:7], v[22:23], v[6:7], v[38:39]
	v_pk_fma_f32 v[2:3], v[24:25], v[2:3], v[42:43]
	v_cvt_pk_bf16_f32 v18, v4, v5
	v_cvt_pk_bf16_f32 v19, v6, v7
	v_cvt_pk_bf16_f32 v20, v0, v1
	v_cvt_pk_bf16_f32 v21, v2, v3
	flat_store_dwordx4 v[44:45], v[18:21]
	s_cbranch_vccnz .LBB0_389
	s_nop 0
	v_lshl_add_u64 v[18:19], s[12:13], 0, v[152:153]
	flat_store_dwordx4 v[18:19], v[4:7] offset:2048 nt
	flat_store_dwordx4 v[18:19], v[0:3] offset:2064 nt
	s_branch .LBB0_389
